# SSD chunk loop S1: x causal conv + SiLU re-emitted with packed f32 ops (v_pk_fma taps, pk add/mul in SiLU), 24 fewer VALU per chunk per wave; same f32 math on bf16 inputs
# baseline (speedup 1.0000x reference)
; #define LAS __attribute__((address_space(3)))
; __device__ __forceinline__ bf16_t f2bf(float f) { return (bf16_t)(pk2(f, 0.f) & 0xffffu); }
; __device__ __forceinline__ float bflo(unsigned w) { return __uint_as_float(w << 16); }
; __device__ __forceinline__ float bfhi(unsigned w) { return __uint_as_float(w & 0xffff0000u); }
; __device__ __forceinline__ float siluf_(float x) { return x * __builtin_amdgcn_rcpf(1.f + __expf(-x)); }
; __device__ __forceinline__ void ssd_item(const Args& a, LAS unsigned char* lds, int layer, bool is_sample, int b, int h, int seq_row0, int nchunks,
;                                          bf16_t* proj, float* ssq, const int tid) {
;     ...
;         {
;             float o[8];
; #pragma unroll
;             for (int i = 0; i < 8; ++i) o[i] = cb[i];
; #pragma unroll
;             for (int k = 0; k < 4; ++k) { const u32x4 w = *(const LAS u32x4*)(lds + L_XRAW + (lane + k) * P64 + wave * 16);
;                 o[0] += cw[k][0] * bflo(w.x); o[1] += cw[k][1] * bfhi(w.x); o[2] += cw[k][2] * bflo(w.y); o[3] += cw[k][3] * bfhi(w.y);
;                 o[4] += cw[k][4] * bflo(w.z); o[5] += cw[k][5] * bfhi(w.z); o[6] += cw[k][6] * bflo(w.w); o[7] += cw[k][7] * bfhi(w.w); }
; #pragma unroll
;             for (int i = 0; i < 8; ++i) *(LAS bf16_t*)(lds + L_XST + (wave * 8 + i) * P64 + lane * 2) = f2bf(siluf_(o[i]));
;         }
.LBB0_570:
	ds_read_b128 v[176:179], v123
	ds_read_b128 v[180:183], v123 offset:144
	ds_read_b128 v[184:187], v123 offset:288
	ds_read_b128 v[188:191], v123 offset:432
	s_add_i32 s65, s15, 0
	s_add_i32 s65, s65, 0x1c73c
	v_add_u32_e32 v164, v110, v192
	v_add_u32_e32 v149, s15, v120
	v_add_u32_e32 v151, s15, v119
	v_mov_b32_e32 v148, s65
	v_add_u32_e32 v150, 0x1a640, v149
	v_add_u32_e32 v149, 0x1c640, v149
	v_add_u32_e32 v152, 0x1a640, v151
	v_add_u32_e32 v151, 0x1c640, v151
	ds_read_b32 v148, v148
	ds_read_b32 v150, v150
	ds_read_b32 v149, v149
	ds_read_b32 v152, v152
	ds_read_b32 v151, v151
	v_add_u32_e32 v165, s15, v117
	s_waitcnt lgkmcnt(8)
	v_lshlrev_b32_e32 v216, 16, v176
	v_and_b32_e32 v217, 0xffff0000, v176
	v_lshlrev_b32_e32 v218, 16, v177
	v_and_b32_e32 v219, 0xffff0000, v177
	v_lshlrev_b32_e32 v220, 16, v178
	v_and_b32_e32 v221, 0xffff0000, v178
	v_lshlrev_b32_e32 v222, 16, v179
	v_and_b32_e32 v223, 0xffff0000, v179
	v_pk_fma_f32 v[102:103], v[6:7], v[216:217], v[38:39]
	v_pk_fma_f32 v[156:157], v[8:9], v[218:219], v[40:41]
	v_pk_fma_f32 v[158:159], v[2:3], v[220:221], v[34:35]
	v_pk_fma_f32 v[160:161], v[4:5], v[222:223], v[36:37]
	s_waitcnt lgkmcnt(7)
	v_lshlrev_b32_e32 v216, 16, v180
	v_and_b32_e32 v217, 0xffff0000, v180
	v_lshlrev_b32_e32 v218, 16, v181
	v_and_b32_e32 v219, 0xffff0000, v181
	v_lshlrev_b32_e32 v220, 16, v182
	v_and_b32_e32 v221, 0xffff0000, v182
	v_lshlrev_b32_e32 v222, 16, v183
	v_and_b32_e32 v223, 0xffff0000, v183
	v_pk_fma_f32 v[102:103], v[10:11], v[216:217], v[102:103]
	v_pk_fma_f32 v[156:157], v[12:13], v[218:219], v[156:157]
	v_pk_fma_f32 v[158:159], v[14:15], v[220:221], v[158:159]
	v_pk_fma_f32 v[160:161], v[16:17], v[222:223], v[160:161]
	s_waitcnt lgkmcnt(6)
	v_lshlrev_b32_e32 v216, 16, v184
	v_and_b32_e32 v217, 0xffff0000, v184
	v_lshlrev_b32_e32 v218, 16, v185
	v_and_b32_e32 v219, 0xffff0000, v185
	v_lshlrev_b32_e32 v220, 16, v186
	v_and_b32_e32 v221, 0xffff0000, v186
	v_lshlrev_b32_e32 v222, 16, v187
	v_and_b32_e32 v223, 0xffff0000, v187
	v_pk_fma_f32 v[102:103], v[18:19], v[216:217], v[102:103]
	v_pk_fma_f32 v[156:157], v[20:21], v[218:219], v[156:157]
	v_pk_fma_f32 v[158:159], v[22:23], v[220:221], v[158:159]
	v_pk_fma_f32 v[160:161], v[24:25], v[222:223], v[160:161]
	s_waitcnt lgkmcnt(5)
	v_lshlrev_b32_e32 v216, 16, v188
	v_and_b32_e32 v217, 0xffff0000, v188
	v_lshlrev_b32_e32 v218, 16, v189
	v_and_b32_e32 v219, 0xffff0000, v189
	v_lshlrev_b32_e32 v220, 16, v190
	v_and_b32_e32 v221, 0xffff0000, v190
	v_lshlrev_b32_e32 v222, 16, v191
	v_and_b32_e32 v223, 0xffff0000, v191
	v_pk_fma_f32 v[102:103], v[26:27], v[216:217], v[102:103]
	v_pk_fma_f32 v[156:157], v[28:29], v[218:219], v[156:157]
	v_pk_fma_f32 v[158:159], v[30:31], v[220:221], v[158:159]
	v_pk_fma_f32 v[160:161], v[32:33], v[222:223], v[160:161]
	v_mul_f32_e32 v224, 0xbfb8aa3b, v102
	v_mul_f32_e32 v225, 0xbfb8aa3b, v103
	v_mul_f32_e32 v226, 0xbfb8aa3b, v156
	v_mul_f32_e32 v227, 0xbfb8aa3b, v157
	v_mul_f32_e32 v228, 0xbfb8aa3b, v158
	v_mul_f32_e32 v229, 0xbfb8aa3b, v159
	v_mul_f32_e32 v230, 0xbfb8aa3b, v160
	v_mul_f32_e32 v231, 0xbfb8aa3b, v161
	v_exp_f32_e32 v224, v224
	v_exp_f32_e32 v225, v225
	v_exp_f32_e32 v226, v226
	v_exp_f32_e32 v227, v227
	v_exp_f32_e32 v228, v228
	v_exp_f32_e32 v229, v229
	v_exp_f32_e32 v230, v230
	v_exp_f32_e32 v231, v231
	v_pk_add_f32 v[224:225], v[224:225], 1.0 op_sel_hi:[1,0]
	v_pk_add_f32 v[226:227], v[226:227], 1.0 op_sel_hi:[1,0]
	v_pk_add_f32 v[228:229], v[228:229], 1.0 op_sel_hi:[1,0]
	v_pk_add_f32 v[230:231], v[230:231], 1.0 op_sel_hi:[1,0]
	v_rcp_f32_e32 v224, v224
	v_rcp_f32_e32 v225, v225
	v_rcp_f32_e32 v226, v226
	v_rcp_f32_e32 v227, v227
	v_rcp_f32_e32 v228, v228
	v_rcp_f32_e32 v229, v229
	v_rcp_f32_e32 v230, v230
	v_rcp_f32_e32 v231, v231
	v_pk_mul_f32 v[102:103], v[102:103], v[224:225]
	v_pk_mul_f32 v[156:157], v[156:157], v[226:227]
	v_pk_mul_f32 v[158:159], v[158:159], v[228:229]
	v_pk_mul_f32 v[160:161], v[160:161], v[230:231]
	v_cvt_pk_bf16_f32 v232, v102, v1
	v_cvt_pk_bf16_f32 v233, v103, v1
	v_cvt_pk_bf16_f32 v234, v156, v1
	v_cvt_pk_bf16_f32 v235, v157, v1
	v_cvt_pk_bf16_f32 v236, v158, v1
	v_cvt_pk_bf16_f32 v237, v159, v1
	v_cvt_pk_bf16_f32 v238, v160, v1
	v_cvt_pk_bf16_f32 v239, v161, v1
	ds_write_b16 v124, v232
	ds_write_b16 v124, v233 offset:144
	ds_write_b16 v124, v234 offset:288
	ds_write_b16 v124, v235 offset:432
	ds_write_b16 v194, v236 offset:576
	ds_write_b16 v194, v237 offset:720
	ds_write_b16 v194, v238 offset:864
	ds_write_b16 v194, v239 offset:1008
	s_waitcnt lgkmcnt(12)
	s_waitcnt lgkmcnt(10)
	v_sub_f32_e32 v103, v148, v149
	s_waitcnt lgkmcnt(8)
	v_sub_f32_e32 v148, v148, v151
	v_exp_f32_e32 v103, v103
	v_exp_f32_e32 v148, v148
	v_mul_f32_e32 v102, v150, v103
	v_mul_f32_e32 v103, v152, v148
	v_lshlrev_b32_e32 v148, 16, v58
	v_lshlrev_b32_e32 v149, 16, v62
	v_and_b32_e32 v58, 0xffff0000, v58
	v_and_b32_e32 v62, 0xffff0000, v62
	v_mul_f32_e32 v58, v102, v58
	v_mul_f32_e32 v62, v103, v62
	v_mul_f32_e32 v148, v102, v148
	v_cvt_pk_bf16_f32 v58, v58, v62
	v_add_u32_e32 v62, 0xd000, v125
	v_mul_f32_e32 v149, v103, v149
	v_cvt_pk_bf16_f32 v148, v148, v149
	ds_write2_b32 v62, v148, v58 offset1:36
	v_lshlrev_b32_e32 v58, 16, v59
	v_and_b32_e32 v59, 0xffff0000, v59
	v_mul_f32_e32 v58, v102, v58
	v_lshlrev_b32_e32 v148, 16, v63
	v_mul_f32_e32 v59, v102, v59
	v_and_b32_e32 v63, 0xffff0000, v63
	v_mul_f32_e32 v148, v103, v148
	v_cvt_pk_bf16_f32 v58, v58, v148
	v_mul_f32_e32 v63, v103, v63
	v_cvt_pk_bf16_f32 v59, v59, v63
	ds_write2_b32 v62, v58, v59 offset0:72 offset1:108
	v_lshlrev_b32_e32 v58, 16, v60
	v_lshlrev_b32_e32 v59, 16, v64
	v_mul_f32_e32 v58, v102, v58
	v_mul_f32_e32 v59, v103, v59
	v_cvt_pk_bf16_f32 v58, v58, v59
	v_and_b32_e32 v59, 0xffff0000, v60
	v_mul_f32_e32 v59, v102, v59
	v_and_b32_e32 v60, 0xffff0000, v64
	v_mul_f32_e32 v60, v103, v60
	v_cvt_pk_bf16_f32 v59, v59, v60
	ds_write2_b32 v62, v58, v59 offset0:144 offset1:180
	v_lshlrev_b32_e32 v58, 16, v61
	v_lshlrev_b32_e32 v59, 16, v65
	v_mul_f32_e32 v58, v102, v58
	v_mul_f32_e32 v59, v103, v59
	v_cvt_pk_bf16_f32 v58, v58, v59
	v_and_b32_e32 v59, 0xffff0000, v61
	v_mul_f32_e32 v59, v102, v59
	v_and_b32_e32 v60, 0xffff0000, v65
	v_mul_f32_e32 v60, v103, v60
	v_cvt_pk_bf16_f32 v59, v59, v60
	ds_write2_b32 v62, v58, v59 offset0:216 offset1:252
	ds_read_b128 v[58:61], v164 offset:18432
	v_add_u32_e32 v102, v111, v192
	ds_read_b128 v[62:65], v102 offset:35840
	ds_read_b128 v[148:151], v164 offset:18496
	ds_read_b128 v[152:155], v164 offset:18624
	s_waitcnt lgkmcnt(2)
; #define LAS __attribute__((address_space(3)))
; __device__ __forceinline__ void ssd_item(const Args& a, LAS unsigned char* lds, int layer, bool is_sample, int b, int h, int seq_row0, int nchunks,
;                                          bf16_t* proj, float* ssq, const int tid) {
;     ...
;         {
;             const int oc = tid & 15, tk = (tid >> 4) * 2;
;             const float a63s = acv[63]; const float wa = dtv[tk] * __builtin_amdgcn_exp2f(a63s - acv[tk]), wb = dtv[tk + 1] * __builtin_amdgcn_exp2f(a63s - acv[tk + 1]);
;             LAS unsigned char* d = lds + L_BWT + (oc * 8) * P64 + ((((tk >> 3) ^ ((oc >> 1) & 7)) << 4) | ((tk * 2) & 15));
;             *(LAS unsigned*)(d + 0 * P64) = pk2(bflo(bo0.x) * wa, bflo(bo1.x) * wb); *(LAS unsigned*)(d + 1 * P64) = pk2(bfhi(bo0.x) * wa, bfhi(bo1.x) * wb);
;             *(LAS unsigned*)(d + 2 * P64) = pk2(bflo(bo0.y) * wa, bflo(bo1.y) * wb); *(LAS unsigned*)(d + 3 * P64) = pk2(bfhi(bo0.y) * wa, bfhi(bo1.y) * wb);
;             *(LAS unsigned*)(d + 4 * P64) = pk2(bflo(bo0.z) * wa, bflo(bo1.z) * wb); *(LAS unsigned*)(d + 5 * P64) = pk2(bfhi(bo0.z) * wa, bfhi(bo1.z) * wb);
;             *(LAS unsigned*)(d + 6 * P64) = pk2(bflo(bo0.w) * wa, bflo(bo1.w) * wb); *(LAS unsigned*)(d + 7 * P64) = pk2(bfhi(bo0.w) * wa, bfhi(bo1.w) * wb);
;         }
;         {
;             float al[4];
; #pragma unroll
;             for (int j = 0; j < 4; ++j) al[j] = acv[16 * rb + 4 * fq + j];
; #pragma unroll
;             for (int ci = 0; ci < 2; ++ci) { const int cbk = (wave & 1) * 2 + ci; f32x4 acc = (f32x4){0.f, 0.f, 0.f, 0.f};
; #pragma unroll
;                 for (int ks = 0; ks < 4; ++ks) { const bf16x8 av = *(const LAS bf16x8*)(lds + L_CM + (16 * rb + fr) * P128 + (32 * ks + 8 * fq) * 2);
;                     const bf16x8 bv = *(const LAS bf16x8*)(lds + L_BM + (16 * cbk + fr) * P128 + (32 * ks + 8 * fq) * 2); acc = mfma16(av, bv, acc); }
;                 const int s = 16 * cbk + fr; const float as = acv[s], ds = dtv[s];
; #pragma unroll
;                 for (int j = 0; j < 4; ++j) { const int l = 16 * rb + 4 * fq + j;
;                     const float gv = (s <= l) ? acc[j] * __builtin_amdgcn_exp2f(al[j] - as) * ds : 0.f;
;                     *(LAS bf16_t*)(lds + L_G + l * P64 + s * 2) = f2bf(gv); } }
;         }
;         LBAR();
;         {
;             float sq[4] = {0.f, 0.f, 0.f, 0.f}, el[4];
; #pragma unroll
	v_mfma_f32_16x16x32_bf16 v[58:61], v[58:61], v[62:65], 0
	ds_read_b128 v[62:65], v164 offset:18560
	ds_read_b128 v[156:159], v102 offset:35904
	ds_read_b128 v[160:163], v102 offset:35968
	v_add_u32_e32 v103, s15, v118
	v_add_u32_e32 v103, 0x1c640, v103
	s_waitcnt lgkmcnt(1)
	v_mfma_f32_16x16x32_bf16 v[58:61], v[148:151], v[156:159], v[58:61]
	ds_read_b128 v[148:151], v103
	v_add_u32_e32 v157, 0x1a640, v165
	v_add_u32_e32 v158, 0x1c680, v165
	s_waitcnt lgkmcnt(1)
	v_mfma_f32_16x16x32_bf16 v[58:61], v[62:65], v[160:163], v[58:61]
	v_add_u32_e32 v62, 0x1c640, v165
	ds_read_b32 v156, v62
	ds_read_b128 v[62:65], v102 offset:36032
	ds_read_b32 v102, v157
	ds_read_b32 v169, v158
	s_waitcnt lgkmcnt(2)
	v_mfma_f32_16x16x32_bf16 v[58:61], v[152:155], v[62:65], v[58:61]
	v_sub_f32_e32 v157, v148, v156
	v_exp_f32_e32 v157, v157
	v_sub_f32_e32 v62, v149, v156
	v_exp_f32_e32 v62, v62
	v_add_u32_e32 v63, v112, v195
	s_nop 2
	v_mul_f32_e32 v58, v58, v157
	s_waitcnt lgkmcnt(1)
	v_mul_f32_e32 v58, v102, v58
	v_cndmask_b32_e64 v58, v58, 0, s[40:41]
	v_cvt_pk_bf16_f32 v58, v58, v1
	ds_write_b16 v63, v58 offset:9216
	v_mul_f32_e32 v58, v59, v62
	v_sub_f32_e32 v59, v150, v156
	v_exp_f32_e32 v59, v59
	v_mul_f32_e32 v58, v102, v58
	v_cndmask_b32_e64 v58, v58, 0, s[42:43]
	v_cvt_pk_bf16_f32 v58, v58, v1
	ds_write_b16 v63, v58 offset:9360
	v_mul_f32_e32 v58, v60, v59
	v_sub_f32_e32 v59, v151, v156
	v_exp_f32_e32 v59, v59
	v_mul_f32_e32 v58, v102, v58
	v_cndmask_b32_e64 v58, v58, 0, s[44:45]
	v_cvt_pk_bf16_f32 v58, v58, v1
	ds_write_b16 v63, v58 offset:9504
	v_mul_f32_e32 v58, v61, v59
	v_mul_f32_e32 v58, v102, v58
	v_cndmask_b32_e64 v58, v58, 0, s[46:47]
	v_cvt_pk_bf16_f32 v58, v58, v1
	ds_write_b16 v63, v58 offset:9648
	ds_read_b128 v[58:61], v164 offset:18432
	v_add_u32_e32 v102, v114, v192
	ds_read_b128 v[62:65], v164 offset:18496
	ds_read_b128 v[152:155], v102 offset:35840
	ds_read_b128 v[156:159], v102 offset:35904
	s_waitcnt lgkmcnt(1)
	v_mfma_f32_16x16x32_bf16 v[58:61], v[58:61], v[152:155], 0
	ds_read_b128 v[152:155], v164 offset:18560
	s_waitcnt lgkmcnt(1)
	v_mfma_f32_16x16x32_bf16 v[58:61], v[62:65], v[156:159], v[58:61]
	ds_read_b128 v[62:65], v102 offset:35968
	ds_read_b128 v[156:159], v164 offset:18624
	ds_read_b128 v[160:163], v102 offset:36032
	s_waitcnt lgkmcnt(2)
	v_mfma_f32_16x16x32_bf16 v[58:61], v[152:155], v[62:65], v[58:61]
	v_sub_f32_e32 v63, v148, v169
	v_add_u32_e32 v62, 0x1a680, v165
	v_exp_f32_e32 v63, v63
	s_waitcnt lgkmcnt(0)
	v_mfma_f32_16x16x32_bf16 v[58:61], v[156:159], v[160:163], v[58:61]
	ds_read_b32 v62, v62
	v_add_u32_e32 v64, v115, v195
	s_nop 5
	v_mul_f32_e32 v58, v58, v63
	v_sub_f32_e32 v63, v149, v169
	v_exp_f32_e32 v63, v63
	s_waitcnt lgkmcnt(0)
	v_mul_f32_e32 v58, v62, v58
	v_cndmask_b32_e64 v58, v58, 0, s[48:49]
	v_cvt_pk_bf16_f32 v58, v58, v1
	ds_write_b16 v64, v58 offset:9216
	v_mul_f32_e32 v58, v59, v63
	v_sub_f32_e32 v59, v150, v169
	v_exp_f32_e32 v59, v59
	v_mul_f32_e32 v58, v62, v58
	v_cndmask_b32_e64 v58, v58, 0, s[50:51]
	v_cvt_pk_bf16_f32 v58, v58, v1
	ds_write_b16 v64, v58 offset:9360
	v_mul_f32_e32 v58, v60, v59
	v_sub_f32_e32 v59, v151, v169
	v_exp_f32_e32 v59, v59
	v_mul_f32_e32 v58, v62, v58
	v_cndmask_b32_e64 v58, v58, 0, s[52:53]
	v_cvt_pk_bf16_f32 v58, v58, v1
	ds_write_b16 v64, v58 offset:9504
	v_mul_f32_e32 v58, v61, v59
	v_mul_f32_e32 v58, v62, v58
	v_cndmask_b32_e64 v58, v58, 0, s[54:55]
	v_cvt_pk_bf16_f32 v58, v58, v1
	ds_write_b16 v64, v58 offset:9648
	s_waitcnt lgkmcnt(0)
	s_barrier
	v_mov_b32_e32 v58, s65
	ds_read_b32 v102, v58
	ds_read_b128 v[148:151], v147
	ds_read_b128 v[176:179], v137 offset:53248
	ds_read_b128 v[180:183], v139 offset:53248
	ds_read_b128 v[184:187], v141 offset:53248
	ds_read_b128 v[188:191], v143 offset:53248
	ds_read_b128 v[152:155], v147 offset:64
	ds_read_b128 v[216:219], v138 offset:53248
	ds_read_b128 v[220:223], v140 offset:53248
	ds_read_b128 v[224:227], v142 offset:53248
	ds_read_b128 v[228:231], v144 offset:53248
	ds_read_b128 v[156:159], v147 offset:9216
	ds_read_b128 v[160:163], v147 offset:9280
	s_waitcnt lgkmcnt(12)
	v_exp_f32_e32 v102, v102
	s_nop 0
	v_pk_mul_f32 v[66:67], v[66:67], v[102:103] op_sel_hi:[1,0]
	v_pk_mul_f32 v[68:69], v[68:69], v[102:103] op_sel_hi:[1,0]
	v_pk_mul_f32 v[78:79], v[78:79], v[102:103] op_sel_hi:[1,0]
	v_pk_mul_f32 v[80:81], v[80:81], v[102:103] op_sel_hi:[1,0]
	v_pk_mul_f32 v[70:71], v[70:71], v[102:103] op_sel_hi:[1,0]
	v_pk_mul_f32 v[72:73], v[72:73], v[102:103] op_sel_hi:[1,0]
	v_pk_mul_f32 v[74:75], v[74:75], v[102:103] op_sel_hi:[1,0]
	v_pk_mul_f32 v[76:77], v[76:77], v[102:103] op_sel_hi:[1,0]
	s_waitcnt lgkmcnt(11)
	s_waitcnt lgkmcnt(10)
	v_mfma_f32_16x16x32_bf16 v[66:69], v[176:179], v[148:151], v[66:69]
	s_waitcnt lgkmcnt(9)
	v_mfma_f32_16x16x32_bf16 v[78:81], v[180:183], v[148:151], v[78:81]
	s_waitcnt lgkmcnt(8)
	v_mfma_f32_16x16x32_bf16 v[70:73], v[184:187], v[148:151], v[70:73]
	s_waitcnt lgkmcnt(7)
	v_mfma_f32_16x16x32_bf16 v[74:77], v[188:191], v[148:151], v[74:77]
	ds_read_b128 v[232:235], v164 offset:18432
	ds_read_b128 v[236:239], v164 offset:18496
	ds_read_b128 v[240:243], v164 offset:18560
	ds_read_b128 v[244:247], v164 offset:18624
	ds_read_b128 v[176:179], v127
	ds_read_b128 v[180:183], v127 offset:64
	ds_read_b128 v[184:187], v127 offset:128
	ds_read_b128 v[188:191], v127 offset:192
	s_waitcnt lgkmcnt(14)
	s_waitcnt lgkmcnt(13)
	v_mfma_f32_16x16x32_bf16 v[66:69], v[216:219], v[152:155], v[66:69]
	s_waitcnt lgkmcnt(12)
	v_mfma_f32_16x16x32_bf16 v[78:81], v[220:223], v[152:155], v[78:81]
	s_waitcnt lgkmcnt(11)
	v_mfma_f32_16x16x32_bf16 v[70:73], v[224:227], v[152:155], v[70:73]
	s_waitcnt lgkmcnt(10)
; #define LAS __attribute__((address_space(3)))
; __device__ __forceinline__ bf16_t f2bf(float f) { return (bf16_t)(pk2(f, 0.f) & 0xffffu); }
; __device__ __forceinline__ float bflo(unsigned w) { return __uint_as_float(w << 16); }
; __device__ __forceinline__ float bfhi(unsigned w) { return __uint_as_float(w & 0xffff0000u); }
; __device__ __forceinline__ void ssd_item(const Args& a, LAS unsigned char* lds, int layer, bool is_sample, int b, int h, int seq_row0, int nchunks,
;                                          bf16_t* proj, float* ssq, const int tid) {
;     ...
;             float sq[4] = {0.f, 0.f, 0.f, 0.f}, el[4];
; #pragma unroll
;             for (int j = 0; j < 4; ++j) el[j] = __builtin_amdgcn_exp2f(acv[16 * rb + 4 * fq + j]);
; #pragma unroll
;             for (int ci = 0; ci < 2; ++ci) { const int cbk = (wave & 1) * 2 + ci; f32x4 acc = (f32x4){0.f, 0.f, 0.f, 0.f}, acp = (f32x4){0.f, 0.f, 0.f, 0.f};
; #pragma unroll
;                 for (int ks = 0; ks < 2; ++ks) { const bf16x8 av = *(const LAS bf16x8*)(lds + L_G + (16 * rb + fr) * P64 + (32 * ks + 8 * fq) * 2);
;                     const bf16x8 bv = *(const LAS bf16x8*)(lds + L_XST + (16 * cbk + fr) * P64 + (32 * ks + 8 * fq) * 2); acc = mfma16(av, bv, acc); }
; #pragma unroll
;                 for (int ks = 0; ks < 4; ++ks) { const bf16x8 av = *(const LAS bf16x8*)(lds + L_CM + (16 * rb + fr) * P128 + (32 * ks + 8 * fq) * 2);
;                     const bf16x8 bv = *(const LAS bf16x8*)(lds + L_ST + (16 * cbk + fr) * P128 + (32 * ks + 8 * fq) * 2); acp = mfma16(av, bv, acp); }
;                 const int p = 16 * cbk + fr;
;                 const u32x2 xs4 = *(const LAS u32x2*)(lds + L_XST + p * P64 + (16 * rb + 4 * fq) * 2);
;                 const float xsv[4] = {bflo(xs4.x), bfhi(xs4.x), bflo(xs4.y), bfhi(xs4.y)};
; #pragma unroll
;                 for (int j = 0; j < 4; ++j) { const int l = 16 * rb + 4 * fq + j;
;                     LAS bf16_t* zp = (LAS bf16_t*)(lds + L_ZT + l * P64 + p * 2);
;                     const float z = bf2f(*zp);
;                     const float yg = (acc[j] + el[j] * acp[j] + xsv[j] * dsk) * siluf_(z);
;                     *zp = f2bf(yg); sq[j] += yg * yg; } }
; #pragma unroll
;             for (int j = 0; j < 4; ++j) { const float v = row16_sum(sq[j]);
;                 if (fr == 0) ssqp[(16 * rb + 4 * fq + j) * 2 + (wave & 1)] = v; }
	v_mfma_f32_16x16x32_bf16 v[74:77], v[228:231], v[152:155], v[74:77]
	ds_read_b128 v[148:151], v126
	ds_read_b128 v[152:155], v126 offset:64
	ds_read_b64 v[248:249], v128
	ds_read_b64 v[250:251], v128 offset:2304
	s_waitcnt lgkmcnt(7)
	v_mfma_f32_16x16x32_bf16 v[176:179], v[232:235], v[176:179], 0
	ds_read_b128 v[216:219], v131
	ds_read_b128 v[220:223], v131 offset:64
	ds_read_b128 v[224:227], v131 offset:128
	ds_read_b128 v[228:231], v131 offset:192
	ds_read_b128 v[58:61], v130
	ds_read_b128 v[62:65], v130 offset:64
	s_waitcnt lgkmcnt(12)
	v_mfma_f32_16x16x32_bf16 v[176:179], v[236:239], v[180:183], v[176:179]
	s_waitcnt lgkmcnt(11)
	v_mfma_f32_16x16x32_bf16 v[176:179], v[240:243], v[184:187], v[176:179]
	s_waitcnt lgkmcnt(10)
	v_mfma_f32_16x16x32_bf16 v[176:179], v[244:247], v[188:191], v[176:179]
	s_waitcnt lgkmcnt(9)
	v_mfma_f32_16x16x32_bf16 v[148:151], v[156:159], v[148:151], 0
	ds_read_u16 v165, v129
	ds_read_u16 v169, v129 offset:144
	ds_read_u16 v170, v129 offset:288
	ds_read_u16 v171, v129 offset:432
	s_waitcnt lgkmcnt(12)
	v_mfma_f32_16x16x32_bf16 v[148:151], v[160:163], v[152:155], v[148:151]
	s_waitcnt lgkmcnt(9)
	v_mfma_f32_16x16x32_bf16 v[216:219], v[232:235], v[216:219], 0
	ds_read_b128 v[232:235], v103
	ds_read_u16 v172, v132
	ds_read_u16 v173, v132 offset:144
	ds_read_u16 v215, v132 offset:288
	ds_read_u16 v102, v132 offset:432
	s_waitcnt lgkmcnt(13)
	v_mfma_f32_16x16x32_bf16 v[216:219], v[236:239], v[220:223], v[216:219]
	s_waitcnt lgkmcnt(10)
	v_mfma_f32_16x16x32_bf16 v[58:61], v[156:159], v[58:61], 0
	s_waitcnt lgkmcnt(9)
	v_mfma_f32_16x16x32_bf16 v[58:61], v[160:163], v[62:65], v[58:61]
	s_waitcnt lgkmcnt(4)
	v_exp_f32_e32 v232, v232
	v_exp_f32_e32 v233, v233
	v_exp_f32_e32 v234, v234
	v_exp_f32_e32 v235, v235
	v_mfma_f32_16x16x32_bf16 v[216:219], v[240:243], v[224:227], v[216:219]
	v_lshlrev_b32_e32 v180, 16, v248
	v_and_b32_e32 v181, 0xffff0000, v248
	v_lshlrev_b32_e32 v182, 16, v249
	v_and_b32_e32 v183, 0xffff0000, v249
	v_mfma_f32_16x16x32_bf16 v[216:219], v[244:247], v[228:231], v[216:219]
	v_lshlrev_b32_e32 v184, 16, v165
	v_lshlrev_b32_e32 v185, 16, v169
	v_lshlrev_b32_e32 v186, 16, v170
	v_lshlrev_b32_e32 v187, 16, v171
	v_mul_f32_e32 v188, 0xbfb8aa3b, v184
	v_mul_f32_e32 v189, 0xbfb8aa3b, v185
	v_mul_f32_e32 v190, 0xbfb8aa3b, v186
	v_mul_f32_e32 v191, 0xbfb8aa3b, v187
	v_exp_f32_e32 v188, v188
	v_exp_f32_e32 v189, v189
	v_exp_f32_e32 v190, v190
	v_exp_f32_e32 v191, v191
	v_pk_fma_f32 v[148:149], v[232:233], v[176:177], v[148:149]
	v_pk_fma_f32 v[150:151], v[234:235], v[178:179], v[150:151]
	v_pk_fma_f32 v[148:149], v[180:181], v[94:95], v[148:149] op_sel:[0,1,0] op_sel_hi:[1,1,1]
	v_pk_fma_f32 v[150:151], v[182:183], v[94:95], v[150:151] op_sel:[0,1,0] op_sel_hi:[1,1,1]
	v_pk_add_f32 v[188:189], v[188:189], 1.0 op_sel_hi:[1,0]
	v_pk_add_f32 v[190:191], v[190:191], 1.0 op_sel_hi:[1,0]
	v_rcp_f32_e32 v188, v188
	v_rcp_f32_e32 v189, v189
	v_rcp_f32_e32 v190, v190
	v_rcp_f32_e32 v191, v191
	v_pk_mul_f32 v[188:189], v[188:189], v[184:185]
	v_pk_mul_f32 v[190:191], v[190:191], v[186:187]
	v_pk_mul_f32 v[152:153], v[148:149], v[188:189]
	v_pk_mul_f32 v[154:155], v[150:151], v[190:191]
	v_cvt_pk_bf16_f32 v176, v152, v1
	ds_write_b16 v129, v176
	v_cvt_pk_bf16_f32 v177, v153, v1
	ds_write_b16 v129, v177 offset:144
	v_cvt_pk_bf16_f32 v178, v154, v1
	ds_write_b16 v129, v178 offset:288
	v_cvt_pk_bf16_f32 v179, v155, v1
	ds_write_b16 v129, v179 offset:432
	v_lshlrev_b32_e32 v184, 16, v250
	v_and_b32_e32 v185, 0xffff0000, v250
	v_lshlrev_b32_e32 v186, 16, v251
	v_and_b32_e32 v187, 0xffff0000, v251
	s_waitcnt lgkmcnt(7)
	v_lshlrev_b32_e32 v180, 16, v172
	s_waitcnt lgkmcnt(6)
	v_lshlrev_b32_e32 v181, 16, v173
	s_waitcnt lgkmcnt(5)
	v_lshlrev_b32_e32 v182, 16, v215
	s_waitcnt lgkmcnt(4)
	v_lshlrev_b32_e32 v183, 16, v102
	v_mul_f32_e32 v188, 0xbfb8aa3b, v180
	v_mul_f32_e32 v189, 0xbfb8aa3b, v181
	v_mul_f32_e32 v190, 0xbfb8aa3b, v182
	v_mul_f32_e32 v191, 0xbfb8aa3b, v183
	v_exp_f32_e32 v188, v188
	v_exp_f32_e32 v189, v189
	v_exp_f32_e32 v190, v190
	v_exp_f32_e32 v191, v191
	v_pk_fma_f32 v[58:59], v[232:233], v[216:217], v[58:59]
	v_pk_fma_f32 v[60:61], v[234:235], v[218:219], v[60:61]
	v_pk_fma_f32 v[58:59], v[184:185], v[94:95], v[58:59] op_sel:[0,1,0] op_sel_hi:[1,1,1]
	v_pk_fma_f32 v[60:61], v[186:187], v[94:95], v[60:61] op_sel:[0,1,0] op_sel_hi:[1,1,1]
	v_pk_add_f32 v[188:189], v[188:189], 1.0 op_sel_hi:[1,0]
	v_pk_add_f32 v[190:191], v[190:191], 1.0 op_sel_hi:[1,0]
	v_rcp_f32_e32 v188, v188
	v_rcp_f32_e32 v189, v189
	v_rcp_f32_e32 v190, v190
	v_rcp_f32_e32 v191, v191
	v_pk_mul_f32 v[188:189], v[188:189], v[180:181]
	v_pk_mul_f32 v[190:191], v[190:191], v[182:183]
	v_pk_mul_f32 v[62:63], v[58:59], v[188:189]
	v_pk_mul_f32 v[64:65], v[60:61], v[190:191]
	v_cvt_pk_bf16_f32 v220, v62, v1
	ds_write_b16 v132, v220
	v_cvt_pk_bf16_f32 v221, v63, v1
	ds_write_b16 v132, v221 offset:144
	v_cvt_pk_bf16_f32 v222, v64, v1
	ds_write_b16 v132, v222 offset:288
	v_cvt_pk_bf16_f32 v223, v65, v1
	ds_write_b16 v132, v223 offset:432
	v_pk_mul_f32 v[156:157], v[62:63], v[62:63]
	v_pk_mul_f32 v[158:159], v[64:65], v[64:65]
	v_pk_fma_f32 v[156:157], v[152:153], v[152:153], v[156:157]
	v_pk_fma_f32 v[158:159], v[154:155], v[154:155], v[158:159]
	s_nop 0
	v_add_f32_dpp v156, v156, v156 quad_perm:[1,0,3,2] row_mask:0xf bank_mask:0xf bound_ctrl:1
	v_add_f32_dpp v157, v157, v157 quad_perm:[1,0,3,2] row_mask:0xf bank_mask:0xf bound_ctrl:1
	v_add_f32_dpp v158, v158, v158 quad_perm:[1,0,3,2] row_mask:0xf bank_mask:0xf bound_ctrl:1
	v_add_f32_dpp v159, v159, v159 quad_perm:[1,0,3,2] row_mask:0xf bank_mask:0xf bound_ctrl:1
	v_add_f32_dpp v156, v156, v156 quad_perm:[2,3,0,1] row_mask:0xf bank_mask:0xf bound_ctrl:1
	v_add_f32_dpp v157, v157, v157 quad_perm:[2,3,0,1] row_mask:0xf bank_mask:0xf bound_ctrl:1
	v_add_f32_dpp v158, v158, v158 quad_perm:[2,3,0,1] row_mask:0xf bank_mask:0xf bound_ctrl:1
	v_add_f32_dpp v159, v159, v159 quad_perm:[2,3,0,1] row_mask:0xf bank_mask:0xf bound_ctrl:1
	v_add_f32_dpp v156, v156, v156 row_half_mirror row_mask:0xf bank_mask:0xf bound_ctrl:1
	v_add_f32_dpp v157, v157, v157 row_half_mirror row_mask:0xf bank_mask:0xf bound_ctrl:1
	v_add_f32_dpp v158, v158, v158 row_half_mirror row_mask:0xf bank_mask:0xf bound_ctrl:1
	v_add_f32_dpp v159, v159, v159 row_half_mirror row_mask:0xf bank_mask:0xf bound_ctrl:1
	v_mov_b32_dpp v160, v156 row_mirror row_mask:0xf bank_mask:0xf bound_ctrl:1
	v_mov_b32_dpp v161, v157 row_mirror row_mask:0xf bank_mask:0xf bound_ctrl:1
	v_mov_b32_dpp v162, v158 row_mirror row_mask:0xf bank_mask:0xf bound_ctrl:1
	v_mov_b32_dpp v163, v159 row_mirror row_mask:0xf bank_mask:0xf bound_ctrl:1
	s_and_saveexec_b64 s[20:21], s[6:7]
	v_add_f32_e32 v156, v156, v160
	v_add_f32_e32 v157, v157, v161
	v_add_f32_e32 v158, v158, v162
	v_add_f32_e32 v159, v159, v163
	ds_write_b32 v133, v156
	ds_write_b32 v134, v157
	ds_write_b32 v135, v158
	ds_write_b32 v136, v159
	s_or_b64 exec, exec, s[20:21]
	s_waitcnt lgkmcnt(0)
	s_barrier
; #define LAS __attribute__((address_space(3)))
; __device__ __forceinline__ void ssd_item(const Args& a, LAS unsigned char* lds, int layer, bool is_sample, int b, int h, int seq_row0, int nchunks,
;                                          bf16_t* proj, float* ssq, const int tid) {
;     ...
;         if (tid < 64) ((LAS float*)(lds + L_SSQA))[c * 64 + tid] = ssqp[tid * 2] + ssqp[tid * 2 + 1];
;     }
	s_and_saveexec_b64 s[20:21], s[38:39]
	s_cbranch_execz .LBB0_560
	s_nop 1
	ds_read_b64 v[58:59], v145
	v_add_u32_e32 v60, s15, v116
	s_waitcnt lgkmcnt(0)
	v_add_f32_e32 v58, v58, v59
	ds_write_b32 v60, v58
	s_branch .LBB0_560
